# compressed pass B: V fragment reads of each PV half issued together with counted lgkmcnt waits
# baseline (speedup 1.0000x reference)
.LBB0_837:
	s_or_b64 exec, exec, s[2:3]
	v_cvt_pk_bf16_f32 v72, v72, v74
	v_cvt_pk_bf16_f32 v73, v75, v198
	v_cvt_pk_bf16_f32 v74, v64, v65
	v_cvt_pk_bf16_f32 v75, v66, v67
	ds_read2_b64 v[204:207], v189 offset0:8 offset1:12
	ds_read2_b64 v[208:211], v191 offset0:40 offset1:44
	ds_read2_b64 v[220:223], v192 offset0:72 offset1:76
	ds_read2_b64 v[224:227], v190 offset0:104 offset1:108
	s_add_i32 s33, s33, 1
	s_add_i32 s2, s39, s33
	v_add_u32_e32 v159, 64, v159
	v_add_u32_e32 v160, 64, v160
	s_waitcnt lgkmcnt(3)
	v_mfma_f32_16x16x32_bf16 v[60:63], v[204:207], v[68:71], v[60:63]
	v_add_u32_e32 v161, 64, v161
	v_subrev_u32_e32 v158, 64, v158
	v_subrev_u32_e32 v113, 64, v113
	v_mfma_f32_16x16x32_bf16 v[44:47], v[204:207], v[72:75], v[44:47]
	s_cmp_lg_u32 s2, 2
	s_waitcnt lgkmcnt(2)
	v_mfma_f32_16x16x32_bf16 v[56:59], v[208:211], v[68:71], v[56:59]
	v_mfma_f32_16x16x32_bf16 v[40:43], v[208:211], v[72:75], v[40:43]
	s_waitcnt lgkmcnt(1)
	v_mfma_f32_16x16x32_bf16 v[52:55], v[220:223], v[68:71], v[52:55]
	v_mfma_f32_16x16x32_bf16 v[36:39], v[220:223], v[72:75], v[36:39]
	s_waitcnt lgkmcnt(0)
	s_barrier
	v_mfma_f32_16x16x32_bf16 v[48:51], v[224:227], v[68:71], v[48:51]
	v_mfma_f32_16x16x32_bf16 v[32:35], v[224:227], v[72:75], v[32:35]
	s_cbranch_scc0 .LBB0_854

.LBB0_846:
	s_or_b64 exec, exec, s[2:3]
	v_lshl_add_u32 v190, s40, 1, v131
	v_add_u32_e32 v189, 0x4800, v190
	v_cvt_pk_bf16_f32 v72, v72, v73
	v_cvt_pk_bf16_f32 v73, v74, v75
	v_cvt_pk_bf16_f32 v74, v64, v65
	v_cvt_pk_bf16_f32 v75, v66, v67
	ds_read2_b64 v[204:207], v189 offset1:4
	s_waitcnt lgkmcnt(2)
	v_add_u32_e32 v191, 0x5000, v190
	s_waitcnt lgkmcnt(1)
	v_add_u32_e32 v192, 0x5800, v190
	v_add_u32_e32 v190, 0x6000, v190
	ds_read2_b64 v[208:211], v191 offset0:32 offset1:36
	ds_read2_b64 v[220:223], v192 offset0:64 offset1:68
	ds_read2_b64 v[224:227], v190 offset0:96 offset1:100
	v_cmp_le_i32_e32 vcc, v98, v113
	s_waitcnt lgkmcnt(3)
	v_mfma_f32_16x16x32_bf16 v[60:63], v[204:207], v[68:71], v[60:63]
	v_mfma_f32_16x16x32_bf16 v[44:47], v[204:207], v[72:75], v[44:47]
	s_waitcnt lgkmcnt(2)
	v_mfma_f32_16x16x32_bf16 v[56:59], v[208:211], v[68:71], v[56:59]
	v_mfma_f32_16x16x32_bf16 v[40:43], v[208:211], v[72:75], v[40:43]
	s_waitcnt lgkmcnt(1)
	v_mfma_f32_16x16x32_bf16 v[52:55], v[220:223], v[68:71], v[52:55]
	v_mfma_f32_16x16x32_bf16 v[36:39], v[220:223], v[72:75], v[36:39]
	s_waitcnt lgkmcnt(0)
	v_mfma_f32_16x16x32_bf16 v[48:51], v[224:227], v[68:71], v[48:51]
	v_mfma_f32_16x16x32_bf16 v[32:35], v[224:227], v[72:75], v[32:35]
	ds_read_b128 v[64:67], v188 offset:4608
	ds_read_b128 v[68:71], v188 offset:4672
	s_waitcnt lgkmcnt(1)
	v_mfma_f32_16x16x32_bf16 v[72:75], v[64:67], v[0:3], 0
	s_waitcnt lgkmcnt(0)
	v_mfma_f32_16x16x32_bf16 v[194:197], v[68:71], v[4:7], v[72:75]
	v_mfma_f32_16x16x32_bf16 v[64:67], v[64:67], v[8:11], 0
	v_mfma_f32_16x16x32_bf16 v[68:71], v[68:71], v[12:15], v[64:67]
	s_nop 6
	ds_read_b128 v[64:67], v188 offset:6912
	ds_read_b128 v[198:201], v188 offset:6976
	v_add_f32_e32 v188, v186, v194
	v_exp_f32_e32 v188, v188
	v_add_f32_e32 v193, v186, v195
	v_exp_f32_e32 v193, v193
	v_add_f32_e32 v194, v186, v196
	v_exp_f32_e32 v194, v194
	v_add_f32_e32 v195, v186, v197
	v_exp_f32_e32 v195, v195
	s_waitcnt lgkmcnt(1)
	v_mfma_f32_16x16x32_bf16 v[72:75], v[64:67], v[0:3], 0
	v_cndmask_b32_e32 v188, 0, v188, vcc
	v_cmp_le_i32_e32 vcc, v100, v113
	v_mfma_f32_16x16x32_bf16 v[64:67], v[64:67], v[8:11], 0
	s_nop 0
	v_cndmask_b32_e32 v193, 0, v193, vcc
	v_cmp_le_i32_e32 vcc, v102, v113
	v_add_f32_e32 v196, v188, v193
	s_waitcnt lgkmcnt(0)
	v_mfma_f32_16x16x32_bf16 v[72:75], v[198:201], v[4:7], v[72:75]
	v_cndmask_b32_e32 v194, 0, v194, vcc
	v_cmp_le_i32_e32 vcc, v120, v113
	v_add_f32_e32 v196, v194, v196
	v_mfma_f32_16x16x32_bf16 v[64:67], v[198:201], v[12:15], v[64:67]
	v_cndmask_b32_e32 v195, 0, v195, vcc
	v_mul_f32_e32 v198, 0.5, v195
	v_fmac_f32_e32 v196, 0.5, v195
	s_nop 1
	v_mov_b32_dpp v197, v196 quad_perm:[1,0,3,2] row_mask:0xf bank_mask:0xf
	v_mov_b32_dpp v198, v198 quad_perm:[1,0,3,2] row_mask:0xf bank_mask:0xf
	s_waitcnt lgkmcnt(1)
	v_add_f32_e32 v196, v196, v197
	s_waitcnt lgkmcnt(0)
	v_fmac_f32_e32 v198, 0.5, v195
	s_nop 1
	v_mov_b32_dpp v197, v196 quad_perm:[2,3,0,1] row_mask:0xf bank_mask:0xf
	v_mov_b32_dpp v199, v198 quad_perm:[2,3,0,1] row_mask:0xf bank_mask:0xf
	s_and_saveexec_b64 s[2:3], s[4:5]
	s_cbranch_execz .LBB0_848
	s_waitcnt lgkmcnt(1)
	v_add_f32_e32 v196, v196, v197
	s_waitcnt lgkmcnt(0)
	v_add_f32_e32 v197, v198, v199
	ds_write_b32 v161, v196 offset:32
	ds_write_b32 v160, v197 offset:32
